# gemm1 tile order: co-resident workgroups (b, b+256) no longer share the weight tile (column tile index xor 32)
# speedup vs baseline: 1.0019x; 1.0019x over previous
.LBB0_192:
	v_mov_b32_e32 v0, v1
	s_mul_hi_i32 s23, s22, 0x2e8ba2e9
	v_mbcnt_lo_u32_b32 v0, -1, v0
	v_mbcnt_hi_u32_b32 v0, -1, v0
	s_lshr_b32 s24, s23, 31
	s_ashr_i32 s23, s23, 3
	v_add_u32_e32 v90, s80, v0
	s_add_i32 s23, s23, s24
	s_mov_b32 s98, s23
	s_mul_i32 s24, s98, 44
	s_sub_i32 s25, s22, s24
	s_mul_i32 s24, s98, 88
	s_add_i32 s24, s24, s25
	s_lshl_b32 s23, s98, 1
	s_lshl_b32 s99, s24, 6
	s_lshl_b32 s25, s25, 6
	s_lshl_b32 s24, s23, 7
	v_lshlrev_b32_e32 v0, 3, v90
	v_ashrrev_i32_e32 v89, 3, v90
	v_and_b32_e32 v88, 56, v0
	s_waitcnt lgkmcnt(0)
	v_lshrrev_b32_e32 v84, 2, v90
	v_lshrrev_b32_e32 v85, 6, v90
	v_lshl_add_u32 v84, v85, 4, v84
	v_bfe_u32 v85, v90, 4, 2
	v_and_b32_e32 v86, 3, v90
	v_xor_b32_e32 v85, v85, v86
	v_lshlrev_b32_e32 v85, 4, v85
	v_add_u32_e32 v86, s24, v84
	v_lshl_or_b32 v66, v86, 11, v85
	v_add_u32_e32 v68, 0x8000, v66
	v_add_u32_e32 v70, 0x40000, v66
	v_add_u32_e32 v72, 0x48000, v66
	s_lshr_b32 vcc_lo, s80, 6
	s_and_b32 vcc_hi, vcc_lo, 1
	s_mul_i32 vcc_hi, vcc_hi, 0xb00
	s_lshr_b32 vcc_lo, vcc_lo, 1
	s_lshl_b32 vcc_lo, vcc_lo, 5
	s_add_i32 vcc_lo, vcc_lo, vcc_hi
	s_add_i32 vcc_lo, vcc_lo, s25
	v_bfe_u32 v86, v90, 2, 4
	v_add_u32_e32 v86, vcc_lo, v86
	v_lshl_or_b32 v74, v86, 11, v85
	v_add_u32_e32 v76, 0x8000, v74
	v_mov_b32_e32 v67, 0
	v_mov_b32_e32 v69, 0
	v_mov_b32_e32 v71, 0
	v_mov_b32_e32 v73, 0
	v_mov_b32_e32 v75, 0
	v_mov_b32_e32 v77, 0
	v_lshl_add_u64 v[66:67], v[66:67], 0, s[72:73]
	v_lshl_add_u64 v[68:69], v[68:69], 0, s[72:73]
	v_lshl_add_u64 v[70:71], v[70:71], 0, s[72:73]
	v_lshl_add_u64 v[72:73], v[72:73], 0, s[72:73]
	v_lshl_add_u64 v[74:75], v[74:75], 0, s[4:5]
	v_lshl_add_u64 v[76:77], v[76:77], 0, s[4:5]
	v_mov_b32_e32 v84, 64
	v_mov_b32_e32 v85, 0
	v_lshl_add_u64 v[126:127], v[66:67], 0, v[84:85]
	v_lshl_add_u64 v[128:129], v[68:69], 0, v[84:85]
	v_lshl_add_u64 v[130:131], v[70:71], 0, v[84:85]
	v_lshl_add_u64 v[132:133], v[72:73], 0, v[84:85]
	v_lshl_add_u64 v[244:245], v[74:75], 0, v[84:85]
	v_lshl_add_u64 v[246:247], v[76:77], 0, v[84:85]
	v_bfe_u32 v84, v90, 5, 1
	v_bfe_u32 v85, v90, 2, 2
	v_xor_b32_e32 v84, v84, v85
	v_lshlrev_b32_e32 v84, 4, v84
	v_lshrrev_b32_e32 v85, 1, v90
	v_and_b32_e32 v85, 64, v85
	v_and_b32_e32 v86, 31, v90
	v_or_b32_e32 v85, v85, v86
	v_lshl_or_b32 v78, v85, 6, v84
	v_xor_b32_e32 v79, 32, v78
	v_and_b32_e32 v85, 0x5f, v90
	v_lshl_or_b32 v80, v85, 6, v84
	v_add_u32_e32 v80, 0x4000, v80
	v_xor_b32_e32 v81, 32, v80
	v_mov_b32_e32 v82, 0x80
	v_mov_b32_e32 v83, 0
	s_lshl_b32 vcc_lo, s80, 5
	v_ashrrev_i32_e32 v2, 1, v90
	v_and_b32_e32 v91, 0xffffffc0, v2
	v_and_b32_e32 v0, 31, v90
	v_mov_b32_e32 v34, 0
	v_mov_b32_e32 v35, 0
	v_mov_b32_e32 v36, 0
	v_mov_b32_e32 v37, 0
	v_mov_b32_e32 v38, 0
	v_mov_b32_e32 v39, 0
	v_mov_b32_e32 v40, 0
	v_mov_b32_e32 v41, 0
	v_mov_b32_e32 v42, 0
	v_mov_b32_e32 v43, 0
	v_mov_b32_e32 v44, 0
	v_mov_b32_e32 v45, 0
	v_mov_b32_e32 v46, 0
	v_mov_b32_e32 v47, 0
	v_mov_b32_e32 v48, 0
	v_mov_b32_e32 v49, 0
	v_mov_b32_e32 v50, 0
	v_mov_b32_e32 v51, 0
	v_mov_b32_e32 v52, 0
	v_mov_b32_e32 v53, 0
	v_mov_b32_e32 v54, 0
	v_mov_b32_e32 v55, 0
	v_mov_b32_e32 v56, 0
	v_mov_b32_e32 v57, 0
	v_mov_b32_e32 v58, 0
	v_mov_b32_e32 v59, 0
	v_mov_b32_e32 v60, 0
	v_mov_b32_e32 v61, 0
	v_mov_b32_e32 v62, 0
	v_mov_b32_e32 v63, 0
	v_mov_b32_e32 v64, 0
	v_mov_b32_e32 v65, 0
	v_mov_b32_e32 v2, 0
	v_mov_b32_e32 v3, 0
	v_mov_b32_e32 v4, 0
	v_mov_b32_e32 v5, 0
	v_mov_b32_e32 v6, 0
	v_mov_b32_e32 v7, 0
	v_mov_b32_e32 v8, 0
	v_mov_b32_e32 v9, 0
	v_mov_b32_e32 v10, 0
	v_mov_b32_e32 v11, 0
	v_mov_b32_e32 v12, 0
	v_mov_b32_e32 v13, 0
	v_mov_b32_e32 v14, 0
	v_mov_b32_e32 v15, 0
	v_mov_b32_e32 v16, 0
	v_mov_b32_e32 v17, 0
	v_mov_b32_e32 v18, 0
	v_mov_b32_e32 v19, 0
	v_mov_b32_e32 v20, 0
	v_mov_b32_e32 v21, 0
	v_mov_b32_e32 v22, 0
	v_mov_b32_e32 v23, 0
	v_mov_b32_e32 v24, 0
	v_mov_b32_e32 v25, 0
	v_mov_b32_e32 v26, 0
	v_mov_b32_e32 v27, 0
	v_mov_b32_e32 v28, 0
	v_mov_b32_e32 v29, 0
	v_mov_b32_e32 v30, 0
	v_mov_b32_e32 v31, 0
	v_mov_b32_e32 v32, 0
	v_mov_b32_e32 v33, 0
	v_mov_b32_e32 v94, 0
	v_mov_b32_e32 v95, 0
	v_mov_b32_e32 v96, 0
	v_mov_b32_e32 v97, 0
	v_mov_b32_e32 v98, 0
	v_mov_b32_e32 v99, 0
	v_mov_b32_e32 v100, 0
	v_mov_b32_e32 v101, 0
	v_mov_b32_e32 v102, 0
	v_mov_b32_e32 v103, 0
	v_mov_b32_e32 v104, 0
	v_mov_b32_e32 v105, 0
	v_mov_b32_e32 v106, 0
	v_mov_b32_e32 v107, 0
	v_mov_b32_e32 v108, 0
	v_mov_b32_e32 v109, 0
	v_mov_b32_e32 v110, 0
	v_mov_b32_e32 v111, 0
	v_mov_b32_e32 v112, 0
	v_mov_b32_e32 v113, 0
	v_mov_b32_e32 v114, 0
	v_mov_b32_e32 v115, 0
	v_mov_b32_e32 v116, 0
	v_mov_b32_e32 v117, 0
	v_mov_b32_e32 v118, 0
	v_mov_b32_e32 v119, 0
	v_mov_b32_e32 v120, 0
	v_mov_b32_e32 v121, 0
	v_mov_b32_e32 v122, 0
	v_mov_b32_e32 v123, 0
	v_mov_b32_e32 v124, 0
	v_mov_b32_e32 v125, 0
	v_mov_b32_e32 v134, 0
	v_mov_b32_e32 v135, 0
	v_mov_b32_e32 v136, 0
	v_mov_b32_e32 v137, 0
	v_mov_b32_e32 v138, 0
	v_mov_b32_e32 v139, 0
	v_mov_b32_e32 v140, 0
	v_mov_b32_e32 v141, 0
	v_mov_b32_e32 v142, 0
	v_mov_b32_e32 v143, 0
	v_mov_b32_e32 v144, 0
	v_mov_b32_e32 v145, 0
	v_mov_b32_e32 v146, 0
	v_mov_b32_e32 v147, 0
	v_mov_b32_e32 v148, 0
	v_mov_b32_e32 v149, 0
	v_mov_b32_e32 v150, 0
	v_mov_b32_e32 v151, 0
	v_mov_b32_e32 v152, 0
	v_mov_b32_e32 v153, 0
	v_mov_b32_e32 v154, 0
	v_mov_b32_e32 v155, 0
	v_mov_b32_e32 v156, 0
	v_mov_b32_e32 v157, 0
	v_mov_b32_e32 v158, 0
	v_mov_b32_e32 v159, 0
	v_mov_b32_e32 v160, 0
	v_mov_b32_e32 v161, 0
	v_mov_b32_e32 v162, 0
	v_mov_b32_e32 v163, 0
	v_mov_b32_e32 v164, 0
	v_mov_b32_e32 v165, 0
	s_barrier
	s_mov_b32 m0, vcc_lo
	s_nop 0
	global_load_lds_dwordx4 v[66:67], off
	s_add_u32 m0, vcc_lo, 0x6000
	s_nop 0
	global_load_lds_dwordx4 v[126:127], off
	s_add_u32 m0, vcc_lo, 0x400
	s_nop 0
	global_load_lds_dwordx4 v[68:69], off
	s_add_u32 m0, vcc_lo, 0x6400
	s_nop 0
	global_load_lds_dwordx4 v[128:129], off
	s_add_u32 m0, vcc_lo, 0x2000
	s_nop 0
	global_load_lds_dwordx4 v[70:71], off
	s_add_u32 m0, vcc_lo, 0x8000
	s_nop 0
	global_load_lds_dwordx4 v[130:131], off
	s_add_u32 m0, vcc_lo, 0x2400
	s_nop 0
	global_load_lds_dwordx4 v[72:73], off
	s_add_u32 m0, vcc_lo, 0x8400
	s_nop 0
	global_load_lds_dwordx4 v[132:133], off
	s_add_u32 m0, vcc_lo, 0x4000
	s_nop 0
	global_load_lds_dwordx4 v[74:75], off
	s_add_u32 m0, vcc_lo, 0xa000
	s_nop 0
	global_load_lds_dwordx4 v[244:245], off
	s_add_u32 m0, vcc_lo, 0x4400
	s_nop 0
	global_load_lds_dwordx4 v[76:77], off
	s_add_u32 m0, vcc_lo, 0xa400
	s_nop 0
	global_load_lds_dwordx4 v[246:247], off
	v_lshl_add_u64 v[66:67], v[66:67], 0, v[82:83]
	v_lshl_add_u64 v[68:69], v[68:69], 0, v[82:83]
	v_lshl_add_u64 v[70:71], v[70:71], 0, v[82:83]
	v_lshl_add_u64 v[72:73], v[72:73], 0, v[82:83]
	v_lshl_add_u64 v[74:75], v[74:75], 0, v[82:83]
	v_lshl_add_u64 v[76:77], v[76:77], 0, v[82:83]
	v_lshl_add_u64 v[126:127], v[126:127], 0, v[82:83]
	v_lshl_add_u64 v[128:129], v[128:129], 0, v[82:83]
	v_lshl_add_u64 v[130:131], v[130:131], 0, v[82:83]
	v_lshl_add_u64 v[132:133], v[132:133], 0, v[82:83]
	v_lshl_add_u64 v[244:245], v[244:245], 0, v[82:83]
	v_lshl_add_u64 v[246:247], v[246:247], 0, v[82:83]
	s_waitcnt vmcnt(0)
	s_barrier
	ds_read_b128 v[166:169], v78
	ds_read_b128 v[170:173], v80
	ds_read_b128 v[174:177], v80 offset:2048
	ds_read_b128 v[178:181], v78 offset:2048
	ds_read_b128 v[182:185], v78 offset:8192
	ds_read_b128 v[188:191], v78 offset:10240
	s_waitcnt lgkmcnt(4)
	v_mfma_f32_32x32x16_bf16 v[34:49], v[166:169], v[170:173], v[34:49]
	ds_read_b128 v[192:195], v79
	s_waitcnt lgkmcnt(4)
	v_mfma_f32_32x32x16_bf16 v[50:65], v[166:169], v[174:177], v[50:65]
	ds_read_b128 v[206:209], v81
	s_waitcnt lgkmcnt(4)
	v_mfma_f32_32x32x16_bf16 v[2:17], v[178:181], v[170:173], v[2:17]
	ds_read_b128 v[210:213], v81 offset:2048
	v_mfma_f32_32x32x16_bf16 v[18:33], v[178:181], v[174:177], v[18:33]
	ds_read_b128 v[222:225], v79 offset:2048
	s_waitcnt lgkmcnt(5)
	v_mfma_f32_32x32x16_bf16 v[94:109], v[182:185], v[170:173], v[94:109]
	ds_read_b128 v[236:239], v79 offset:8192
	v_mfma_f32_32x32x16_bf16 v[110:125], v[182:185], v[174:177], v[110:125]
	ds_read_b128 v[240:243], v79 offset:10240
	s_waitcnt lgkmcnt(6)
	v_mfma_f32_32x32x16_bf16 v[134:149], v[188:191], v[170:173], v[134:149]
	v_mfma_f32_32x32x16_bf16 v[150:165], v[188:191], v[174:177], v[150:165]
	s_waitcnt vmcnt(0) lgkmcnt(0)
	s_barrier
	s_mov_b32 vcc_hi, 4

.LBB0_512:
	v_lshrrev_b32_e32 v66, 3, v88
	v_and_or_b32 v66, v66, 4, v90
	s_movk_i32 s22, 0x110
	v_and_or_b32 v0, v88, 64, v0
	v_mul_lo_u32 v66, v66, s22
	v_cvt_pk_bf16_f32 v50, v50, s0
	v_lshl_add_u32 v0, v0, 1, v66
	v_cvt_pk_bf16_f32 v34, v34, s0
	v_cvt_pk_bf16_f32 v18, v18, s0
	v_cvt_pk_bf16_f32 v2, v2, s0
	ds_write_b16 v0, v50
	v_cvt_pk_bf16_f32 v50, v51, s0
	ds_write_b16 v0, v34 offset:64
	v_cvt_pk_bf16_f32 v34, v35, s0
	ds_write_b16 v0, v18 offset:8704
	v_cvt_pk_bf16_f32 v18, v19, s0
	ds_write_b16 v0, v2 offset:8768
	v_cvt_pk_bf16_f32 v2, v3, s0
	ds_write_b16 v0, v50 offset:272
	v_cvt_pk_bf16_f32 v50, v52, s0
	ds_write_b16 v0, v34 offset:336
	v_cvt_pk_bf16_f32 v34, v36, s0
	ds_write_b16 v0, v18 offset:8976
	v_cvt_pk_bf16_f32 v18, v20, s0
	ds_write_b16 v0, v2 offset:9040
	v_cvt_pk_bf16_f32 v2, v4, s0
	ds_write_b16 v0, v50 offset:544
	v_cvt_pk_bf16_f32 v50, v53, s0
	ds_write_b16 v0, v34 offset:608
	v_cvt_pk_bf16_f32 v34, v37, s0
	ds_write_b16 v0, v18 offset:9248
	v_cvt_pk_bf16_f32 v18, v21, s0
	ds_write_b16 v0, v2 offset:9312
	v_cvt_pk_bf16_f32 v2, v5, s0
	ds_write_b16 v0, v50 offset:816
	v_cvt_pk_bf16_f32 v50, v54, s0
	ds_write_b16 v0, v34 offset:880
	v_cvt_pk_bf16_f32 v34, v38, s0
	ds_write_b16 v0, v18 offset:9520
	v_cvt_pk_bf16_f32 v18, v22, s0
	ds_write_b16 v0, v2 offset:9584
	v_cvt_pk_bf16_f32 v2, v6, s0
	ds_write_b16 v0, v50 offset:2176
	v_cvt_pk_bf16_f32 v50, v55, s0
	ds_write_b16 v0, v34 offset:2240
	v_cvt_pk_bf16_f32 v34, v39, s0
	ds_write_b16 v0, v18 offset:10880
	v_cvt_pk_bf16_f32 v18, v23, s0
	ds_write_b16 v0, v2 offset:10944
	v_cvt_pk_bf16_f32 v2, v7, s0
	ds_write_b16 v0, v50 offset:2448
	v_cvt_pk_bf16_f32 v50, v56, s0
	ds_write_b16 v0, v34 offset:2512
	v_cvt_pk_bf16_f32 v34, v40, s0
	ds_write_b16 v0, v18 offset:11152
	v_cvt_pk_bf16_f32 v18, v24, s0
	ds_write_b16 v0, v2 offset:11216
	v_cvt_pk_bf16_f32 v2, v8, s0
	ds_write_b16 v0, v50 offset:2720
	v_cvt_pk_bf16_f32 v50, v57, s0
	ds_write_b16 v0, v34 offset:2784
	v_cvt_pk_bf16_f32 v34, v41, s0
	ds_write_b16 v0, v18 offset:11424
	v_cvt_pk_bf16_f32 v18, v25, s0
	ds_write_b16 v0, v2 offset:11488
	v_cvt_pk_bf16_f32 v2, v9, s0
	ds_write_b16 v0, v50 offset:2992
	v_cvt_pk_bf16_f32 v50, v58, s0
	ds_write_b16 v0, v34 offset:3056
	v_cvt_pk_bf16_f32 v34, v42, s0
	ds_write_b16 v0, v18 offset:11696
	v_cvt_pk_bf16_f32 v18, v26, s0
	ds_write_b16 v0, v2 offset:11760
	v_cvt_pk_bf16_f32 v2, v10, s0
	ds_write_b16 v0, v50 offset:4352
	v_cvt_pk_bf16_f32 v50, v59, s0
	ds_write_b16 v0, v34 offset:4416
	v_cvt_pk_bf16_f32 v34, v43, s0
	ds_write_b16 v0, v18 offset:13056
	v_cvt_pk_bf16_f32 v18, v27, s0
	ds_write_b16 v0, v2 offset:13120
	v_cvt_pk_bf16_f32 v2, v11, s0
	ds_write_b16 v0, v50 offset:4624
	v_cvt_pk_bf16_f32 v50, v60, s0
	ds_write_b16 v0, v34 offset:4688
	v_cvt_pk_bf16_f32 v34, v44, s0
	ds_write_b16 v0, v18 offset:13328
	v_cvt_pk_bf16_f32 v18, v28, s0
	ds_write_b16 v0, v2 offset:13392
	v_cvt_pk_bf16_f32 v2, v12, s0
	ds_write_b16 v0, v50 offset:4896
	v_cvt_pk_bf16_f32 v50, v61, s0
	ds_write_b16 v0, v34 offset:4960
	v_cvt_pk_bf16_f32 v34, v45, s0
	ds_write_b16 v0, v18 offset:13600
	v_cvt_pk_bf16_f32 v18, v29, s0
	ds_write_b16 v0, v2 offset:13664
	v_cvt_pk_bf16_f32 v2, v13, s0
	ds_write_b16 v0, v50 offset:5168
	v_cvt_pk_bf16_f32 v50, v62, s0
	ds_write_b16 v0, v34 offset:5232
	v_cvt_pk_bf16_f32 v34, v46, s0
	ds_write_b16 v0, v18 offset:13872
	v_cvt_pk_bf16_f32 v18, v30, s0
	ds_write_b16 v0, v2 offset:13936
	v_cvt_pk_bf16_f32 v2, v14, s0
	ds_write_b16 v0, v50 offset:6528
	v_cvt_pk_bf16_f32 v50, v63, s0
	ds_write_b16 v0, v34 offset:6592
	v_cvt_pk_bf16_f32 v34, v47, s0
	ds_write_b16 v0, v18 offset:15232
	v_cvt_pk_bf16_f32 v18, v31, s0
	ds_write_b16 v0, v2 offset:15296
	v_cvt_pk_bf16_f32 v2, v15, s0
	ds_write_b16 v0, v50 offset:6800
	v_cvt_pk_bf16_f32 v50, v64, s0
	ds_write_b16 v0, v34 offset:6864
	v_cvt_pk_bf16_f32 v34, v48, s0
	ds_write_b16 v0, v18 offset:15504
	v_cvt_pk_bf16_f32 v18, v32, s0
	ds_write_b16 v0, v2 offset:15568
	v_cvt_pk_bf16_f32 v2, v16, s0
	ds_write_b16 v0, v50 offset:7072
	v_cvt_pk_bf16_f32 v50, v65, s0
	ds_write_b16 v0, v34 offset:7136
	v_cvt_pk_bf16_f32 v34, v49, s0
	ds_write_b16 v0, v18 offset:15776
	v_cvt_pk_bf16_f32 v18, v33, s0
	ds_write_b16 v0, v2 offset:15840
	v_cvt_pk_bf16_f32 v2, v17, s0
	ds_write_b16 v0, v50 offset:7344
	ds_write_b16 v0, v34 offset:7408
	ds_write_b16 v0, v18 offset:16048
	ds_write_b16 v0, v2 offset:16112
	v_ashrrev_i32_e32 v0, 4, v88
	v_and_b32_e32 v6, 0x78, v89
	v_add_u32_e32 v7, s27, v0
	v_mul_lo_u32 v0, v0, s22
	v_lshl_add_u32 v12, v6, 1, v0
	s_waitcnt lgkmcnt(0)
	s_barrier
	ds_read_b128 v[2:5], v12
	v_mul_lo_u32 v0, s29, v7
	v_add3_u32 v0, s28, v6, v0
	v_lshl_add_u64 v[10:11], v[0:1], 1, s[20:21]
	ds_read_b128 v[6:9], v12 offset:4352
	s_waitcnt lgkmcnt(1)
	global_store_dwordx4 v[10:11], v[2:5], off
	ds_read_b128 v[2:5], v12 offset:8704
	s_lshl_b32 s22, s29, 4
	v_add_u32_e32 v0, s22, v0
	v_lshl_add_u64 v[10:11], v[0:1], 1, s[20:21]
	v_add_u32_e32 v0, s22, v0
	s_waitcnt lgkmcnt(1)
	global_store_dwordx4 v[10:11], v[6:9], off
	v_lshl_add_u64 v[10:11], v[0:1], 1, s[20:21]
	ds_read_b128 v[6:9], v12 offset:13056
	s_waitcnt lgkmcnt(1)
	global_store_dwordx4 v[10:11], v[2:5], off
	ds_read_b128 v[2:5], v12 offset:17408
	v_add_u32_e32 v0, s22, v0
	v_lshl_add_u64 v[10:11], v[0:1], 1, s[20:21]
	v_add_u32_e32 v0, s22, v0
	s_waitcnt lgkmcnt(1)
	global_store_dwordx4 v[10:11], v[6:9], off
	v_lshl_add_u64 v[10:11], v[0:1], 1, s[20:21]
	ds_read_b128 v[6:9], v12 offset:21760
	s_waitcnt lgkmcnt(1)
	global_store_dwordx4 v[10:11], v[2:5], off
	ds_read_b128 v[2:5], v12 offset:26112
	v_add_u32_e32 v0, s22, v0
	v_lshl_add_u64 v[10:11], v[0:1], 1, s[20:21]
	v_add_u32_e32 v0, s22, v0
	s_waitcnt lgkmcnt(1)
	global_store_dwordx4 v[10:11], v[6:9], off
	v_lshl_add_u64 v[10:11], v[0:1], 1, s[20:21]
	ds_read_b128 v[6:9], v12 offset:30464
	v_add_u32_e32 v0, s22, v0
	s_waitcnt lgkmcnt(1)
	global_store_dwordx4 v[10:11], v[2:5], off
	s_nop 1
	v_lshl_add_u64 v[2:3], v[0:1], 1, s[20:21]
	s_waitcnt lgkmcnt(0)
	global_store_dwordx4 v[2:3], v[6:9], off
	s_cmp_eq_u32 m0, 0x7ead
	s_cbranch_scc0 .Lg1p_next
	s_mov_b32 m0, 0
	s_nop 1
	v_mov_b32_e32 v50, v94
	v_mov_b32_e32 v51, v95
	v_mov_b32_e32 v52, v96
	v_mov_b32_e32 v53, v97
	v_mov_b32_e32 v54, v98
	v_mov_b32_e32 v55, v99
	v_mov_b32_e32 v56, v100
	v_mov_b32_e32 v57, v101
	v_mov_b32_e32 v58, v102
	v_mov_b32_e32 v59, v103
	v_mov_b32_e32 v60, v104
	v_mov_b32_e32 v61, v105
	v_mov_b32_e32 v62, v106
	v_mov_b32_e32 v63, v107
	v_mov_b32_e32 v64, v108
	v_mov_b32_e32 v65, v109
	v_mov_b32_e32 v34, v110
	v_mov_b32_e32 v35, v111
	v_mov_b32_e32 v36, v112
	v_mov_b32_e32 v37, v113
	v_mov_b32_e32 v38, v114
	v_mov_b32_e32 v39, v115
	v_mov_b32_e32 v40, v116
	v_mov_b32_e32 v41, v117
	v_mov_b32_e32 v42, v118
	v_mov_b32_e32 v43, v119
	v_mov_b32_e32 v44, v120
	v_mov_b32_e32 v45, v121
	v_mov_b32_e32 v46, v122
	v_mov_b32_e32 v47, v123
	v_mov_b32_e32 v48, v124
	v_mov_b32_e32 v49, v125
	v_mov_b32_e32 v18, v134
	v_mov_b32_e32 v19, v135
	v_mov_b32_e32 v20, v136
	v_mov_b32_e32 v21, v137
	v_mov_b32_e32 v22, v138
	v_mov_b32_e32 v23, v139
	v_mov_b32_e32 v24, v140
	v_mov_b32_e32 v25, v141
	v_mov_b32_e32 v26, v142
	v_mov_b32_e32 v27, v143
	v_mov_b32_e32 v28, v144
	v_mov_b32_e32 v29, v145
	v_mov_b32_e32 v30, v146
	v_mov_b32_e32 v31, v147
	v_mov_b32_e32 v32, v148
	v_mov_b32_e32 v33, v149
	v_mov_b32_e32 v2, v150
	v_mov_b32_e32 v3, v151
	v_mov_b32_e32 v4, v152
	v_mov_b32_e32 v5, v153
	v_mov_b32_e32 v6, v154
	v_mov_b32_e32 v7, v155
	v_mov_b32_e32 v8, v156
	v_mov_b32_e32 v9, v157
	v_mov_b32_e32 v10, v158
	v_mov_b32_e32 v11, v159
	v_mov_b32_e32 v12, v160
	v_mov_b32_e32 v13, v161
	v_mov_b32_e32 v14, v162
	v_mov_b32_e32 v15, v163
	v_mov_b32_e32 v16, v164
	v_mov_b32_e32 v17, v165
	v_and_b32_e32 v0, 31, v88
	s_add_i32 s27, s27, 0x80
	s_and_b32 s28, s25, 0x1f80
	s_cmpk_eq_u32 s81, 0x200
	s_cbranch_scc0 .Lg1p_nomap2
	s_and_b32 s28, s26, 63
	s_bfe_u32 vcc_lo, s26, 0x10008
	s_lshl_b32 vcc_lo, vcc_lo, 5
	s_xor_b32 s28, s28, vcc_lo
	s_lshl_b32 s28, s28, 7
.Lg1p_nomap2:
	s_branch .Lg1p_epi

.LBB0_513:
	v_mov_b32_e32 v0, v1
	s_and_b32 s28, s25, 0x1f80
	v_mbcnt_lo_u32_b32 v0, -1, v0
	v_mbcnt_hi_u32_b32 v0, -1, v0
	v_add_u32_e32 v88, s80, v0
	s_lshl_b32 s27, s24, 1
	s_and_b32 s27, s27, 0xffffff00
	s_cmpk_eq_u32 s81, 0x200
	s_cbranch_scc0 .Lg1p_nomap
	s_and_b32 s28, s26, 63
	s_bfe_u32 vcc_lo, s26, 0x10008
	s_lshl_b32 vcc_lo, vcc_lo, 5
	s_xor_b32 s28, s28, vcc_lo
	s_lshl_b32 s28, s28, 7
.Lg1p_nomap:
	s_waitcnt lgkmcnt(0)
	v_lshlrev_b32_e32 v89, 3, v88
	v_lshrrev_b32_e32 v84, 2, v88
	v_lshrrev_b32_e32 v85, 6, v88
	v_lshl_add_u32 v84, v85, 4, v84
	v_bfe_u32 v85, v88, 4, 2
	v_and_b32_e32 v86, 3, v88
	v_xor_b32_e32 v85, v85, v86
	v_lshlrev_b32_e32 v85, 4, v85
	v_add_u32_e32 v86, s27, v84
	v_lshl_or_b32 v66, v86, 11, v85
	v_add_u32_e32 v68, 0x8000, v66
	v_add_u32_e32 v70, 0x40000, v66
	v_add_u32_e32 v72, 0x48000, v66
	v_add_u32_e32 v86, s28, v84
	v_lshl_or_b32 v74, v86, 11, v85
	v_add_u32_e32 v76, 0x8000, v74
	v_mov_b32_e32 v67, 0
	v_mov_b32_e32 v69, 0
	v_mov_b32_e32 v71, 0
	v_mov_b32_e32 v73, 0
	v_mov_b32_e32 v75, 0
	v_mov_b32_e32 v77, 0
	v_lshl_add_u64 v[66:67], v[66:67], 0, s[72:73]
	v_lshl_add_u64 v[68:69], v[68:69], 0, s[72:73]
	v_lshl_add_u64 v[70:71], v[70:71], 0, s[72:73]
	v_lshl_add_u64 v[72:73], v[72:73], 0, s[72:73]
	v_lshl_add_u64 v[74:75], v[74:75], 0, s[4:5]
	v_lshl_add_u64 v[76:77], v[76:77], 0, s[4:5]
	v_mov_b32_e32 v84, 64
	v_mov_b32_e32 v85, 0
	v_lshl_add_u64 v[126:127], v[66:67], 0, v[84:85]
	v_lshl_add_u64 v[128:129], v[68:69], 0, v[84:85]
	v_lshl_add_u64 v[130:131], v[70:71], 0, v[84:85]
	v_lshl_add_u64 v[132:133], v[72:73], 0, v[84:85]
	v_lshl_add_u64 v[244:245], v[74:75], 0, v[84:85]
	v_lshl_add_u64 v[246:247], v[76:77], 0, v[84:85]
	v_bfe_u32 v84, v88, 5, 1
	v_bfe_u32 v85, v88, 2, 2
	v_xor_b32_e32 v84, v84, v85
	v_lshlrev_b32_e32 v84, 4, v84
	v_lshrrev_b32_e32 v85, 1, v88
	v_and_b32_e32 v85, 64, v85
	v_and_b32_e32 v86, 31, v88
	v_or_b32_e32 v85, v85, v86
	v_lshl_or_b32 v78, v85, 6, v84
	v_xor_b32_e32 v79, 32, v78
	v_and_b32_e32 v85, 0x5f, v88
	v_lshl_or_b32 v80, v85, 6, v84
	v_add_u32_e32 v80, 0x4000, v80
	v_xor_b32_e32 v81, 32, v80
	v_mov_b32_e32 v82, 0x80
	v_mov_b32_e32 v83, 0
	s_lshl_b32 vcc_lo, s80, 5
	v_ashrrev_i32_e32 v2, 1, v88
	v_and_b32_e32 v90, 0xffffffc0, v2
	v_and_b32_e32 v0, 31, v88
	v_mov_b32_e32 v50, 0
	v_mov_b32_e32 v51, 0
	v_mov_b32_e32 v52, 0
	v_mov_b32_e32 v53, 0
	v_mov_b32_e32 v54, 0
	v_mov_b32_e32 v55, 0
	v_mov_b32_e32 v56, 0
	v_mov_b32_e32 v57, 0
	v_mov_b32_e32 v58, 0
	v_mov_b32_e32 v59, 0
	v_mov_b32_e32 v60, 0
	v_mov_b32_e32 v61, 0
	v_mov_b32_e32 v62, 0
	v_mov_b32_e32 v63, 0
	v_mov_b32_e32 v64, 0
	v_mov_b32_e32 v65, 0
	v_mov_b32_e32 v34, 0
	v_mov_b32_e32 v35, 0
	v_mov_b32_e32 v36, 0
	v_mov_b32_e32 v37, 0
	v_mov_b32_e32 v38, 0
	v_mov_b32_e32 v39, 0
	v_mov_b32_e32 v40, 0
	v_mov_b32_e32 v41, 0
	v_mov_b32_e32 v42, 0
	v_mov_b32_e32 v43, 0
	v_mov_b32_e32 v44, 0
	v_mov_b32_e32 v45, 0
	v_mov_b32_e32 v46, 0
	v_mov_b32_e32 v47, 0
	v_mov_b32_e32 v48, 0
	v_mov_b32_e32 v49, 0
	v_mov_b32_e32 v18, 0
	v_mov_b32_e32 v19, 0
	v_mov_b32_e32 v20, 0
	v_mov_b32_e32 v21, 0
	v_mov_b32_e32 v22, 0
	v_mov_b32_e32 v23, 0
	v_mov_b32_e32 v24, 0
	v_mov_b32_e32 v25, 0
	v_mov_b32_e32 v26, 0
	v_mov_b32_e32 v27, 0
	v_mov_b32_e32 v28, 0
	v_mov_b32_e32 v29, 0
	v_mov_b32_e32 v30, 0
	v_mov_b32_e32 v31, 0
	v_mov_b32_e32 v32, 0
	v_mov_b32_e32 v33, 0
	v_mov_b32_e32 v2, 0
	v_mov_b32_e32 v3, 0
	v_mov_b32_e32 v4, 0
	v_mov_b32_e32 v5, 0
	v_mov_b32_e32 v6, 0
	v_mov_b32_e32 v7, 0
	v_mov_b32_e32 v8, 0
	v_mov_b32_e32 v9, 0
	v_mov_b32_e32 v10, 0
	v_mov_b32_e32 v11, 0
	v_mov_b32_e32 v12, 0
	v_mov_b32_e32 v13, 0
	v_mov_b32_e32 v14, 0
	v_mov_b32_e32 v15, 0
	v_mov_b32_e32 v16, 0
	v_mov_b32_e32 v17, 0
	v_mov_b32_e32 v94, 0
	v_mov_b32_e32 v95, 0
	v_mov_b32_e32 v96, 0
	v_mov_b32_e32 v97, 0
	v_mov_b32_e32 v98, 0
	v_mov_b32_e32 v99, 0
	v_mov_b32_e32 v100, 0
	v_mov_b32_e32 v101, 0
	v_mov_b32_e32 v102, 0
	v_mov_b32_e32 v103, 0
	v_mov_b32_e32 v104, 0
	v_mov_b32_e32 v105, 0
	v_mov_b32_e32 v106, 0
	v_mov_b32_e32 v107, 0
	v_mov_b32_e32 v108, 0
	v_mov_b32_e32 v109, 0
	v_mov_b32_e32 v110, 0
	v_mov_b32_e32 v111, 0
	v_mov_b32_e32 v112, 0
	v_mov_b32_e32 v113, 0
	v_mov_b32_e32 v114, 0
	v_mov_b32_e32 v115, 0
	v_mov_b32_e32 v116, 0
	v_mov_b32_e32 v117, 0
	v_mov_b32_e32 v118, 0
	v_mov_b32_e32 v119, 0
	v_mov_b32_e32 v120, 0
	v_mov_b32_e32 v121, 0
	v_mov_b32_e32 v122, 0
	v_mov_b32_e32 v123, 0
	v_mov_b32_e32 v124, 0
	v_mov_b32_e32 v125, 0
	v_mov_b32_e32 v134, 0
	v_mov_b32_e32 v135, 0
	v_mov_b32_e32 v136, 0
	v_mov_b32_e32 v137, 0
	v_mov_b32_e32 v138, 0
	v_mov_b32_e32 v139, 0
	v_mov_b32_e32 v140, 0
	v_mov_b32_e32 v141, 0
	v_mov_b32_e32 v142, 0
	v_mov_b32_e32 v143, 0
	v_mov_b32_e32 v144, 0
	v_mov_b32_e32 v145, 0
	v_mov_b32_e32 v146, 0
	v_mov_b32_e32 v147, 0
	v_mov_b32_e32 v148, 0
	v_mov_b32_e32 v149, 0
	v_mov_b32_e32 v150, 0
	v_mov_b32_e32 v151, 0
	v_mov_b32_e32 v152, 0
	v_mov_b32_e32 v153, 0
	v_mov_b32_e32 v154, 0
	v_mov_b32_e32 v155, 0
	v_mov_b32_e32 v156, 0
	v_mov_b32_e32 v157, 0
	v_mov_b32_e32 v158, 0
	v_mov_b32_e32 v159, 0
	v_mov_b32_e32 v160, 0
	v_mov_b32_e32 v161, 0
	v_mov_b32_e32 v162, 0
	v_mov_b32_e32 v163, 0
	v_mov_b32_e32 v164, 0
	v_mov_b32_e32 v165, 0
	s_barrier
	s_mov_b32 m0, vcc_lo
	s_nop 0
	global_load_lds_dwordx4 v[66:67], off
	s_add_u32 m0, vcc_lo, 0x6000
	s_nop 0
	global_load_lds_dwordx4 v[126:127], off
	s_add_u32 m0, vcc_lo, 0x400
	s_nop 0
	global_load_lds_dwordx4 v[68:69], off
	s_add_u32 m0, vcc_lo, 0x6400
	s_nop 0
	global_load_lds_dwordx4 v[128:129], off
	s_add_u32 m0, vcc_lo, 0x2000
	s_nop 0
	global_load_lds_dwordx4 v[70:71], off
	s_add_u32 m0, vcc_lo, 0x8000
	s_nop 0
	global_load_lds_dwordx4 v[130:131], off
	s_add_u32 m0, vcc_lo, 0x2400
	s_nop 0
	global_load_lds_dwordx4 v[72:73], off
	s_add_u32 m0, vcc_lo, 0x8400
	s_nop 0
	global_load_lds_dwordx4 v[132:133], off
	s_add_u32 m0, vcc_lo, 0x4000
	s_nop 0
	global_load_lds_dwordx4 v[74:75], off
	s_add_u32 m0, vcc_lo, 0xa000
	s_nop 0
	global_load_lds_dwordx4 v[244:245], off
	s_add_u32 m0, vcc_lo, 0x4400
	s_nop 0
	global_load_lds_dwordx4 v[76:77], off
	s_add_u32 m0, vcc_lo, 0xa400
	s_nop 0
	global_load_lds_dwordx4 v[246:247], off
	v_lshl_add_u64 v[66:67], v[66:67], 0, v[82:83]
	v_lshl_add_u64 v[68:69], v[68:69], 0, v[82:83]
	v_lshl_add_u64 v[70:71], v[70:71], 0, v[82:83]
	v_lshl_add_u64 v[72:73], v[72:73], 0, v[82:83]
	v_lshl_add_u64 v[74:75], v[74:75], 0, v[82:83]
	v_lshl_add_u64 v[76:77], v[76:77], 0, v[82:83]
	v_lshl_add_u64 v[126:127], v[126:127], 0, v[82:83]
	v_lshl_add_u64 v[128:129], v[128:129], 0, v[82:83]
	v_lshl_add_u64 v[130:131], v[130:131], 0, v[82:83]
	v_lshl_add_u64 v[132:133], v[132:133], 0, v[82:83]
	v_lshl_add_u64 v[244:245], v[244:245], 0, v[82:83]
	v_lshl_add_u64 v[246:247], v[246:247], 0, v[82:83]
	s_waitcnt vmcnt(0)
	s_barrier
	ds_read_b128 v[166:169], v78
	ds_read_b128 v[170:173], v80
	ds_read_b128 v[174:177], v80 offset:2048
	ds_read_b128 v[178:181], v78 offset:2048
	ds_read_b128 v[182:185], v78 offset:8192
	ds_read_b128 v[188:191], v78 offset:10240
	s_waitcnt lgkmcnt(4)
	v_mfma_f32_32x32x16_bf16 v[50:65], v[166:169], v[170:173], v[50:65]
	ds_read_b128 v[192:195], v79
	s_waitcnt lgkmcnt(4)
	v_mfma_f32_32x32x16_bf16 v[34:49], v[166:169], v[174:177], v[34:49]
	ds_read_b128 v[206:209], v81
	s_waitcnt lgkmcnt(4)
	v_mfma_f32_32x32x16_bf16 v[18:33], v[178:181], v[170:173], v[18:33]
	ds_read_b128 v[210:213], v81 offset:2048
	v_mfma_f32_32x32x16_bf16 v[2:17], v[178:181], v[174:177], v[2:17]
	ds_read_b128 v[222:225], v79 offset:2048
	s_waitcnt lgkmcnt(5)
	v_mfma_f32_32x32x16_bf16 v[94:109], v[182:185], v[170:173], v[94:109]
	ds_read_b128 v[236:239], v79 offset:8192
	v_mfma_f32_32x32x16_bf16 v[110:125], v[182:185], v[174:177], v[110:125]
	ds_read_b128 v[240:243], v79 offset:10240
	s_waitcnt lgkmcnt(6)
	v_mfma_f32_32x32x16_bf16 v[134:149], v[188:191], v[170:173], v[134:149]
	v_mfma_f32_32x32x16_bf16 v[150:165], v[188:191], v[174:177], v[150:165]
	s_waitcnt vmcnt(0) lgkmcnt(0)
	s_barrier
	s_mov_b32 vcc_hi, 4
